# nt cache policy on the once-read row loads of the three norm phases and on the final output stores
# baseline (speedup 1.0000x reference)
; template <int MODE> __device__ __forceinline__ void norm_row2(const float* xa, const float* xb, const float* nw, const float* sca, const float* sha, const float* scb, const float* shb, ...
;     const f32x4* pa = (const f32x4*)xa + lane; const f32x4* pb = (const f32x4*)xb + lane;
;     f32x4 va[4], vb[4]; float s0 = 0.f, s1 = 0.f;
; #pragma unroll
;     for (int j = 0; j < 4; ++j) { va[j] = pa[64 * j]; vb[j] = pb[64 * j]; }
; #pragma unroll
;     for (int j = 0; j < 4; ++j) { s0 += (va[j].x * va[j].x + va[j].y * va[j].y) + (va[j].z * va[j].z + va[j].w * va[j].w); s1 += (vb[j].x * vb[j].x + vb[j].y * vb[j].y) + (vb[j].z * vb[j].z + vb[j].w * vb[j].w); }
; #pragma unroll
;     for (int o = 1; o < 64; o <<= 1) { s0 += __shfl_xor(s0, o); s1 += __shfl_xor(s1, o); }
;     const float r0 = 1.f / sqrtf(s0 * (1.f / D) + eps), r1 = 1.f / sqrtf(s1 * (1.f / D) + eps);
; __global__ void __launch_bounds__(512, 2) hymba_fwd(Args a) {
;     ...
;         for (int row = gw; row < TT; row += 2 * NGW) { const int rb_ = row + NGW; const int mb = batch_of_row(row); const float* xr = row < T_P ? a.in[0] + (size_t)row * D : a.in[1] + (size_t)(row - T_P) * D;
;             if (rb_ < TT) { const int mb2 = batch_of_row(rb_); const float* xr2 = rb_ < T_P ? a.in[0] + (size_t)rb_ * D : a.in[1] + (size_t)(rb_ - T_P) * D;
;                 norm_row2<0>(xr, xr2, a.in[6], MOD + mb * 6144 + 1024, MOD + mb * 6144, MOD + mb2 * 6144 + 1024, MOD + mb2 * 6144, XN + (size_t)row * D, XN + (size_t)rb_ * D, nullptr, nullptr, 1e-6f, lane); }
.LBB0_778:
	global_load_dwordx4 v[28:31], v44, s[24:25] nt
	global_load_dwordx4 v[24:27], v44, s[38:39] nt
	global_load_dwordx4 v[20:23], v44, s[24:25] offset:1024 nt
	global_load_dwordx4 v[16:19], v44, s[38:39] offset:1024 nt
	global_load_dwordx4 v[0:3], v44, s[24:25] offset:3072 nt
	global_load_dwordx4 v[8:11], v44, s[24:25] offset:2048 nt
	global_load_dwordx4 v[4:7], v44, s[38:39] offset:3072 nt
	global_load_dwordx4 v[12:15], v44, s[38:39] offset:2048 nt
	v_cmp_lt_i32_e32 vcc, v47, v46
	s_lshr_b32 s6, s6, 11
	s_ashr_i32 s3, s22, 14
	v_cndmask_b32_e32 v60, v45, v47, vcc
	v_cmp_lt_i32_e32 vcc, v48, v46
	v_lshlrev_b32_e32 v83, 2, v60
	s_add_i32 s6, s6, 2
	v_cndmask_b32_e32 v61, v45, v48, vcc
	v_cmp_lt_i32_e32 vcc, v49, v46
	v_lshlrev_b32_e32 v86, 2, v61
	s_and_b64 s[0:1], exec, s[0:1]
	v_cndmask_b32_e32 v62, v45, v49, vcc
	v_cmp_lt_i32_e32 vcc, v50, v46
	v_lshlrev_b32_e32 v87, 2, v62
	s_cselect_b32 s6, s3, s6
	v_cndmask_b32_e32 v63, v45, v50, vcc
	v_cmp_lt_i32_e32 vcc, v51, v46
	v_lshlrev_b32_e32 v88, 2, v63
	s_ashr_i32 s3, s2, 31
	v_cndmask_b32_e32 v64, v45, v51, vcc
	v_cmp_lt_i32_e32 vcc, v52, v46
	v_lshlrev_b32_e32 v89, 2, v64
	s_lshl_b64 s[0:1], s[2:3], 2
	v_cndmask_b32_e32 v65, v45, v52, vcc
	v_lshlrev_b32_e32 v90, 2, v65
	s_add_u32 s22, s34, s0
	s_addc_u32 s23, s35, s1
	s_mul_i32 s2, s6, 0x1800
	s_add_u32 s24, s22, 0x1000
	s_addc_u32 s25, s23, 0
	s_ashr_i32 s3, s2, 31
	s_lshl_b64 s[0:1], s[2:3], 2
	s_add_u32 s38, s34, s0
	s_addc_u32 s39, s35, s1
	global_load_dwordx4 v[56:59], v[32:33], off
	s_add_u32 s42, s38, 0x1000
	s_addc_u32 s43, s39, 0
	s_lshl_b64 s[26:27], s[26:27], 11
	s_waitcnt vmcnt(8)
	v_pk_mul_f32 v[60:61], v[30:31], v[30:31]
	v_pk_mul_f32 v[62:63], v[28:29], v[28:29]
	s_waitcnt vmcnt(7)
	v_pk_mul_f32 v[64:65], v[26:27], v[26:27]
	v_pk_mul_f32 v[66:67], v[24:25], v[24:25]
	s_waitcnt vmcnt(6)
	v_pk_mul_f32 v[68:69], v[22:23], v[22:23]
	v_pk_mul_f32 v[70:71], v[20:21], v[20:21]
	v_pk_mov_b32 v[84:85], v[62:63], v[60:61] op_sel:[1,0]
	v_mov_b32_e32 v63, v61
	v_pk_mov_b32 v[60:61], v[66:67], v[64:65] op_sel:[1,0]
	v_mov_b32_e32 v67, v65
	v_pk_mov_b32 v[64:65], v[70:71], v[68:69] op_sel:[1,0]
	v_mov_b32_e32 v71, v69
	s_waitcnt vmcnt(5)
	v_pk_mul_f32 v[72:73], v[18:19], v[18:19]
	v_pk_mul_f32 v[74:75], v[16:17], v[16:17]
	s_waitcnt vmcnt(3)
	v_mul_f32_e32 v76, v9, v9
	v_mul_f32_e32 v78, v11, v11
	v_pk_add_f32 v[62:63], v[84:85], v[62:63]
	v_pk_add_f32 v[64:65], v[64:65], v[70:71]
	v_mul_f32_e32 v91, v0, v0
	v_mul_f32_e32 v92, v1, v1
	v_mul_f32_e32 v93, v2, v2
	v_mul_f32_e32 v94, v3, v3
	v_pk_mov_b32 v[68:69], v[74:75], v[72:73] op_sel:[1,0]
	v_mov_b32_e32 v75, v73
	v_pk_fma_f32 v[72:73], v[8:9], v[8:9], v[76:77] op_sel_hi:[1,1,0]
	v_pk_fma_f32 v[76:77], v[10:11], v[10:11], v[78:79] op_sel_hi:[1,1,0]
	v_pk_add_f32 v[62:63], v[62:63], v[62:63] op_sel:[0,1] op_sel_hi:[1,0]
	v_pk_add_f32 v[64:65], v[64:65], v[64:65] op_sel:[0,1] op_sel_hi:[1,0]
	v_mov_b32_e32 v73, v93
	v_mov_b32_e32 v77, v94
	v_mov_b32_e32 v63, v91
	v_mov_b32_e32 v65, v92
	v_pk_add_f32 v[60:61], v[60:61], v[66:67]
	v_pk_add_f32 v[66:67], v[68:69], v[74:75]
	v_pk_add_f32 v[68:69], v[72:73], v[76:77]
	v_pk_add_f32 v[62:63], v[62:63], v[64:65]
	s_waitcnt vmcnt(1)
	v_mul_f32_e32 v80, v13, v13
	v_pk_add_f32 v[62:63], v[62:63], v[68:69]
	v_mul_f32_e32 v82, v15, v15
	v_add_f32_e32 v68, v62, v63
	ds_bpermute_b32 v69, v83, v68
	v_pk_add_f32 v[62:63], v[66:67], v[66:67] op_sel:[0,1] op_sel_hi:[1,0]
	v_mul_f32_e32 v95, v4, v4
	v_mul_f32_e32 v96, v5, v5
	v_mul_f32_e32 v97, v6, v6
	s_waitcnt lgkmcnt(0)
	v_add_f32_e32 v66, v68, v69
	ds_bpermute_b32 v67, v86, v66
	v_mul_f32_e32 v98, v7, v7
	v_pk_fma_f32 v[78:79], v[12:13], v[12:13], v[80:81] op_sel_hi:[1,1,0]
	v_pk_fma_f32 v[80:81], v[14:15], v[14:15], v[82:83] op_sel_hi:[1,1,0]
	v_pk_add_f32 v[60:61], v[60:61], v[60:61] op_sel:[0,1] op_sel_hi:[1,0]
	v_mov_b32_e32 v79, v97
	v_mov_b32_e32 v81, v98
	v_mov_b32_e32 v61, v95
	v_mov_b32_e32 v63, v96
	v_pk_add_f32 v[64:65], v[78:79], v[80:81]
	v_pk_add_f32 v[60:61], v[60:61], v[62:63]
	s_waitcnt lgkmcnt(0)
	v_add_f32_e32 v62, v66, v67
	v_pk_add_f32 v[60:61], v[60:61], v[64:65]
	ds_bpermute_b32 v63, v87, v62
	v_add_f32_e32 v60, v60, v61
	ds_bpermute_b32 v61, v83, v60
	s_waitcnt lgkmcnt(1)
	v_add_f32_e32 v70, v62, v63
	ds_bpermute_b32 v71, v88, v70
	s_waitcnt lgkmcnt(1)
	v_add_f32_e32 v68, v60, v61
	ds_bpermute_b32 v69, v86, v68
	global_load_dwordx4 v[60:63], v44, s[24:25]
	global_load_dwordx4 v[64:67], v44, s[22:23]
	s_waitcnt lgkmcnt(1)
	v_add_f32_e32 v70, v70, v71
	ds_bpermute_b32 v71, v89, v70
	s_waitcnt lgkmcnt(1)
	v_add_f32_e32 v68, v68, v69
	ds_bpermute_b32 v69, v87, v68
	s_waitcnt lgkmcnt(1)
	v_add_f32_e32 v70, v70, v71
	ds_bpermute_b32 v71, v90, v70
	s_waitcnt lgkmcnt(1)
	v_add_f32_e32 v68, v68, v69
	ds_bpermute_b32 v69, v88, v68
	s_waitcnt lgkmcnt(0)
	v_add_f32_e32 v76, v68, v69
	v_add_f32_e32 v68, v70, v71
	v_fmamk_f32 v78, v68, 0x3a800000, v42
	global_load_dwordx4 v[68:71], v44, s[42:43]
	global_load_dwordx4 v[72:75], v44, s[38:39]
	v_mul_f32_e32 v79, 0x4f800000, v78
	v_cmp_gt_f32_e32 vcc, s44, v78
	ds_bpermute_b32 v77, v89, v76
	s_waitcnt lgkmcnt(0)
	v_add_f32_e32 v76, v76, v77
	v_cndmask_b32_e32 v78, v78, v79, vcc
	v_sqrt_f32_e32 v79, v78
	ds_bpermute_b32 v77, v90, v76
	v_add_u32_e32 v80, -1, v79
	v_fma_f32 v81, -v80, v79, v78
	v_cmp_ge_f32_e64 s[0:1], 0, v81
	v_add_u32_e32 v81, 1, v79
	s_waitcnt lgkmcnt(0)
; __device__ __forceinline__ unsigned pk2(float lo, float hi) { return f2bf(lo) | (f2bf(hi) << 16); }
; template <int MODE> __device__ __forceinline__ void norm_row2(const float* xa, const float* xb, const float* nw, const float* sca, const float* sha, const float* scb, const float* shb, ...
;     ...
;     const float r0 = 1.f / sqrtf(s0 * (1.f / D) + eps), r1 = 1.f / sqrtf(s1 * (1.f / D) + eps);
; #pragma unroll
;     for (int j = 0; j < 4; ++j) { const f32x4 w = ((const f32x4*)nw)[64 * j + lane]; f32x4 ya = va[j] * r0 * w, yb = vb[j] * r1 * w;
;         if (MODE == 0) { const f32x4 ca = ((const f32x4*)sca)[64 * j + lane], ha = ((const f32x4*)sha)[64 * j + lane], cb = ((const f32x4*)scb)[64 * j + lane], hb = ((const f32x4*)shb)[64 * j + lane];
;             ya = ya * (ca + 1.f) + ha; yb = yb * (cb + 1.f) + hb;
;             u32x2 o; o.x = pk2(ya.x, ya.y); o.y = pk2(ya.z, ya.w); ((u32x2*)oa)[64 * j + lane] = o; o.x = pk2(yb.x, yb.y); o.y = pk2(yb.z, yb.w); ((u32x2*)ob)[64 * j + lane] = o; }
	v_add_f32_e32 v76, v76, v77
	v_cndmask_b32_e64 v80, v79, v80, s[0:1]
	v_fma_f32 v79, -v81, v79, v78
	v_cmp_lt_f32_e64 s[0:1], 0, v79
	v_fmamk_f32 v76, v76, 0x3a800000, v42
	v_mul_f32_e32 v82, 0x4f800000, v76
	v_cndmask_b32_e64 v79, v80, v81, s[0:1]
	v_mul_f32_e32 v80, 0x37800000, v79
	v_cndmask_b32_e32 v79, v79, v80, vcc
	v_cmp_class_f32_e32 vcc, v78, v43
	s_nop 1
	v_cndmask_b32_e32 v78, v79, v78, vcc
	v_div_scale_f32 v79, s[0:1], v78, v78, 1.0
	v_rcp_f32_e32 v80, v79
	v_cmp_gt_f32_e64 s[0:1], s44, v76
	v_fma_f32 v77, -v79, v80, 1.0
	s_nop 0
	v_cndmask_b32_e64 v76, v76, v82, s[0:1]
	v_fmac_f32_e32 v80, v77, v80
	v_div_scale_f32 v77, vcc, 1.0, v78, 1.0
	v_sqrt_f32_e32 v82, v76
	v_mul_f32_e32 v81, v77, v80
	v_fma_f32 v83, -v79, v81, v77
	v_fmac_f32_e32 v81, v83, v80
	v_fma_f32 v77, -v79, v81, v77
	v_add_u32_e32 v79, -1, v82
	v_fma_f32 v83, -v79, v82, v76
	v_cmp_ge_f32_e64 s[2:3], 0, v83
	v_add_u32_e32 v83, 1, v82
	s_nop 0
	v_cndmask_b32_e64 v79, v82, v79, s[2:3]
	v_fma_f32 v82, -v83, v82, v76
	v_cmp_lt_f32_e64 s[2:3], 0, v82
	s_nop 1
	v_cndmask_b32_e64 v79, v79, v83, s[2:3]
	v_mul_f32_e32 v82, 0x37800000, v79
	v_cndmask_b32_e64 v79, v79, v82, s[0:1]
	v_cmp_class_f32_e64 s[0:1], v76, v43
	s_nop 1
	v_cndmask_b32_e64 v79, v79, v76, s[0:1]
	v_div_scale_f32 v82, s[0:1], v79, v79, 1.0
	v_rcp_f32_e32 v83, v82
	v_div_fmas_f32 v76, v77, v80, v81
	v_div_fixup_f32 v76, v76, v78, 1.0
	v_fma_f32 v77, -v82, v83, 1.0
	v_fmac_f32_e32 v83, v77, v83
	v_div_scale_f32 v77, vcc, 1.0, v79, 1.0
	v_mul_f32_e32 v78, v77, v83
	v_fma_f32 v80, -v82, v78, v77
	v_fmac_f32_e32 v78, v80, v83
	v_fma_f32 v77, -v82, v78, v77
	v_div_fmas_f32 v77, v77, v83, v78
	v_div_fixup_f32 v78, v77, v79, 1.0
	v_pk_mul_f32 v[30:31], v[30:31], v[76:77] op_sel_hi:[1,0]
	v_pk_mul_f32 v[28:29], v[28:29], v[76:77] op_sel_hi:[1,0]
	v_pk_mul_f32 v[26:27], v[26:27], v[78:79] op_sel_hi:[1,0]
	v_pk_mul_f32 v[24:25], v[24:25], v[78:79] op_sel_hi:[1,0]
	s_waitcnt vmcnt(4)
	v_pk_mul_f32 v[28:29], v[56:57], v[28:29]
	v_pk_mul_f32 v[30:31], v[58:59], v[30:31]
	v_pk_mul_f32 v[24:25], v[56:57], v[24:25]
	v_pk_mul_f32 v[26:27], v[58:59], v[26:27]
	s_waitcnt vmcnt(3)
	v_pk_add_f32 v[56:57], v[62:63], 1.0 op_sel_hi:[1,0]
	v_pk_add_f32 v[58:59], v[60:61], 1.0 op_sel_hi:[1,0]
	s_waitcnt vmcnt(2)
	v_pk_fma_f32 v[30:31], v[56:57], v[30:31], v[66:67]
	v_pk_fma_f32 v[28:29], v[58:59], v[28:29], v[64:65]
	s_waitcnt vmcnt(1)
	v_pk_add_f32 v[56:57], v[70:71], 1.0 op_sel_hi:[1,0]
	v_pk_add_f32 v[58:59], v[68:69], 1.0 op_sel_hi:[1,0]
	s_waitcnt vmcnt(0)
	v_pk_fma_f32 v[26:27], v[56:57], v[26:27], v[74:75]
	v_bfe_u32 v56, v28, 16, 1
	v_add3_u32 v28, v28, v56, s45
	v_bfe_u32 v56, v29, 16, 1
	v_lshrrev_b32_e32 v28, 16, v28
	v_add3_u32 v29, v29, v56, s45
	v_and_or_b32 v28, v29, s56, v28
	v_bfe_u32 v29, v30, 16, 1
	v_add3_u32 v29, v30, v29, s45
	v_bfe_u32 v30, v31, 16, 1
	v_lshrrev_b32_e32 v29, 16, v29
	v_add3_u32 v30, v31, v30, s45
	v_add_co_u32_e32 v40, vcc, s57, v40
	v_pk_fma_f32 v[24:25], v[58:59], v[24:25], v[72:73]
	v_and_or_b32 v29, v30, s56, v29
	v_addc_co_u32_e32 v41, vcc, 0, v41, vcc
	global_store_dwordx2 v[40:41], v[28:29], off
	v_bfe_u32 v28, v24, 16, 1
	v_add3_u32 v24, v24, v28, s45
	v_bfe_u32 v28, v25, 16, 1
	v_lshrrev_b32_e32 v24, 16, v24
	v_add3_u32 v25, v25, v28, s45
	v_and_or_b32 v24, v25, s56, v24
	v_bfe_u32 v25, v26, 16, 1
	v_add3_u32 v25, v26, v25, s45
	v_bfe_u32 v26, v27, 16, 1
	v_lshrrev_b32_e32 v25, 16, v25
	v_add3_u32 v26, v27, v26, s45
	v_and_or_b32 v25, v26, s56, v25
	v_lshl_add_u64 v[68:69], v[34:35], 0, s[26:27]
	global_store_dwordx2 v[68:69], v[24:25], off
	global_load_dwordx4 v[24:27], v[32:33], off offset:1024
	s_nop 0
	global_load_dwordx4 v[28:31], v53, s[24:25]
	global_load_dwordx4 v[56:59], v44, s[22:23] offset:1024
	global_load_dwordx4 v[60:63], v53, s[42:43]
	global_load_dwordx4 v[64:67], v44, s[38:39] offset:1024
	v_pk_mul_f32 v[22:23], v[22:23], v[76:77] op_sel_hi:[1,0]
	v_pk_mul_f32 v[20:21], v[20:21], v[76:77] op_sel_hi:[1,0]
	v_pk_mul_f32 v[18:19], v[18:19], v[78:79] op_sel_hi:[1,0]
	v_pk_mul_f32 v[16:17], v[16:17], v[78:79] op_sel_hi:[1,0]
	v_pk_mul_f32 v[10:11], v[10:11], v[76:77] op_sel_hi:[1,0]
	v_pk_mul_f32 v[8:9], v[8:9], v[76:77] op_sel_hi:[1,0]
	v_pk_mul_f32 v[14:15], v[14:15], v[78:79] op_sel_hi:[1,0]
	v_pk_mul_f32 v[12:13], v[12:13], v[78:79] op_sel_hi:[1,0]
	v_pk_mul_f32 v[2:3], v[2:3], v[76:77] op_sel_hi:[1,0]
	v_pk_mul_f32 v[0:1], v[0:1], v[76:77] op_sel_hi:[1,0]
	v_pk_mul_f32 v[4:5], v[4:5], v[78:79] op_sel_hi:[1,0]
	v_pk_mul_f32 v[6:7], v[6:7], v[78:79] op_sel_hi:[1,0]
	s_waitcnt vmcnt(4)
; __device__ __forceinline__ unsigned pk2(float lo, float hi) { return f2bf(lo) | (f2bf(hi) << 16); }
; template <int MODE> __device__ __forceinline__ void norm_row2(const float* xa, const float* xb, const float* nw, const float* sca, const float* sha, const float* scb, const float* shb, ...
;     ...
;     for (int j = 0; j < 4; ++j) { const f32x4 w = ((const f32x4*)nw)[64 * j + lane]; f32x4 ya = va[j] * r0 * w, yb = vb[j] * r1 * w;
;         if (MODE == 0) { const f32x4 ca = ((const f32x4*)sca)[64 * j + lane], ha = ((const f32x4*)sha)[64 * j + lane], cb = ((const f32x4*)scb)[64 * j + lane], hb = ((const f32x4*)shb)[64 * j + lane];
;             ya = ya * (ca + 1.f) + ha; yb = yb * (cb + 1.f) + hb;
;             u32x2 o; o.x = pk2(ya.x, ya.y); o.y = pk2(ya.z, ya.w); ((u32x2*)oa)[64 * j + lane] = o; o.x = pk2(yb.x, yb.y); o.y = pk2(yb.z, yb.w); ((u32x2*)ob)[64 * j + lane] = o; }
	v_pk_mul_f32 v[20:21], v[20:21], v[24:25]
	v_pk_mul_f32 v[22:23], v[22:23], v[26:27]
	v_pk_mul_f32 v[16:17], v[24:25], v[16:17]
	v_pk_mul_f32 v[18:19], v[26:27], v[18:19]
	s_waitcnt vmcnt(3)
	v_pk_add_f32 v[24:25], v[30:31], 1.0 op_sel_hi:[1,0]
	v_pk_add_f32 v[26:27], v[28:29], 1.0 op_sel_hi:[1,0]
	s_waitcnt vmcnt(2)
	v_pk_fma_f32 v[22:23], v[22:23], v[24:25], v[58:59]
	v_pk_fma_f32 v[20:21], v[20:21], v[26:27], v[56:57]
	s_waitcnt vmcnt(1)
	v_pk_add_f32 v[24:25], v[62:63], 1.0 op_sel_hi:[1,0]
	v_pk_add_f32 v[26:27], v[60:61], 1.0 op_sel_hi:[1,0]
	s_waitcnt vmcnt(0)
	v_pk_fma_f32 v[18:19], v[18:19], v[24:25], v[66:67]
	v_bfe_u32 v24, v20, 16, 1
	v_add3_u32 v20, v20, v24, s45
	v_bfe_u32 v24, v21, 16, 1
	v_lshrrev_b32_e32 v20, 16, v20
	v_add3_u32 v21, v21, v24, s45
	v_and_or_b32 v20, v21, s56, v20
	v_bfe_u32 v21, v22, 16, 1
	v_add3_u32 v21, v22, v21, s45
	v_bfe_u32 v22, v23, 16, 1
	v_lshrrev_b32_e32 v21, 16, v21
	v_add3_u32 v22, v23, v22, s45
	v_pk_fma_f32 v[16:17], v[16:17], v[26:27], v[64:65]
	v_and_or_b32 v21, v22, s56, v21
	global_store_dwordx2 v[40:41], v[20:21], off offset:512
	v_bfe_u32 v20, v16, 16, 1
	v_add3_u32 v16, v16, v20, s45
	v_bfe_u32 v20, v17, 16, 1
	v_lshrrev_b32_e32 v16, 16, v16
	v_add3_u32 v17, v17, v20, s45
	v_and_or_b32 v16, v17, s56, v16
	v_bfe_u32 v17, v18, 16, 1
	v_add3_u32 v17, v18, v17, s45
	v_bfe_u32 v18, v19, 16, 1
	v_lshrrev_b32_e32 v17, 16, v17
	v_add3_u32 v18, v19, v18, s45
	v_and_or_b32 v17, v18, s56, v17
	global_store_dwordx2 v[68:69], v[16:17], off offset:512
	global_load_dwordx4 v[16:19], v[32:33], off offset:2048
	s_nop 0
	global_load_dwordx4 v[20:23], v54, s[24:25]
	global_load_dwordx4 v[24:27], v54, s[42:43]
	global_load_dwordx4 v[28:31], v44, s[22:23] offset:2048
	global_load_dwordx4 v[56:59], v44, s[38:39] offset:2048
	s_waitcnt vmcnt(4)
	v_pk_mul_f32 v[8:9], v[8:9], v[16:17]
	v_pk_mul_f32 v[10:11], v[10:11], v[18:19]
	v_pk_mul_f32 v[12:13], v[12:13], v[16:17]
	v_pk_mul_f32 v[14:15], v[14:15], v[18:19]
	s_waitcnt vmcnt(3)
	v_pk_add_f32 v[16:17], v[22:23], 1.0 op_sel_hi:[1,0]
	v_pk_add_f32 v[18:19], v[20:21], 1.0 op_sel_hi:[1,0]
	s_waitcnt vmcnt(2)
	v_pk_add_f32 v[20:21], v[26:27], 1.0 op_sel_hi:[1,0]
	v_pk_add_f32 v[22:23], v[24:25], 1.0 op_sel_hi:[1,0]
	s_waitcnt vmcnt(1)
	v_pk_fma_f32 v[10:11], v[10:11], v[16:17], v[30:31]
	v_pk_fma_f32 v[8:9], v[8:9], v[18:19], v[28:29]
	s_waitcnt vmcnt(0)
	v_pk_fma_f32 v[14:15], v[14:15], v[20:21], v[58:59]
	v_pk_fma_f32 v[12:13], v[12:13], v[22:23], v[56:57]
	v_bfe_u32 v16, v8, 16, 1
	v_bfe_u32 v18, v10, 16, 1
	v_bfe_u32 v17, v9, 16, 1
	v_bfe_u32 v19, v11, 16, 1
	v_bfe_u32 v20, v12, 16, 1
	v_bfe_u32 v22, v14, 16, 1
	v_add3_u32 v8, v8, v16, s45
	v_add3_u32 v10, v10, v18, s45
	v_bfe_u32 v21, v13, 16, 1
	v_bfe_u32 v23, v15, 16, 1
	v_add3_u32 v9, v9, v17, s45
	v_add3_u32 v11, v11, v19, s45
	v_add3_u32 v12, v12, v20, s45
	v_add3_u32 v14, v14, v22, s45
	v_lshrrev_b32_e32 v8, 16, v8
	v_lshrrev_b32_e32 v10, 16, v10
	v_add3_u32 v13, v13, v21, s45
	v_add3_u32 v15, v15, v23, s45
	v_lshrrev_b32_e32 v12, 16, v12
	v_lshrrev_b32_e32 v14, 16, v14
	v_and_or_b32 v8, v9, s56, v8
	v_and_or_b32 v9, v11, s56, v10
	v_and_or_b32 v10, v13, s56, v12
	v_and_or_b32 v11, v15, s56, v14
	global_store_dwordx2 v[40:41], v[8:9], off offset:1024
	global_store_dwordx2 v[68:69], v[10:11], off offset:1024
	global_load_dwordx4 v[8:11], v[32:33], off offset:3072
	s_nop 0
	global_load_dwordx4 v[12:15], v55, s[24:25]
	global_load_dwordx4 v[16:19], v55, s[42:43]
	global_load_dwordx4 v[20:23], v44, s[22:23] offset:3072
	global_load_dwordx4 v[24:27], v44, s[38:39] offset:3072
	s_waitcnt vmcnt(4)
	v_pk_mul_f32 v[0:1], v[0:1], v[8:9]
	v_pk_mul_f32 v[2:3], v[2:3], v[10:11]
	v_pk_mul_f32 v[6:7], v[6:7], v[10:11]
	v_pk_mul_f32 v[4:5], v[4:5], v[8:9]
	s_waitcnt vmcnt(3)
	v_pk_add_f32 v[8:9], v[14:15], 1.0 op_sel_hi:[1,0]
	v_pk_add_f32 v[10:11], v[12:13], 1.0 op_sel_hi:[1,0]
	s_waitcnt vmcnt(2)
	v_pk_add_f32 v[12:13], v[18:19], 1.0 op_sel_hi:[1,0]
	v_pk_add_f32 v[14:15], v[16:17], 1.0 op_sel_hi:[1,0]
	s_waitcnt vmcnt(1)
	v_pk_fma_f32 v[8:9], v[2:3], v[8:9], v[22:23]
	v_pk_fma_f32 v[10:11], v[0:1], v[10:11], v[20:21]
	s_waitcnt vmcnt(0)
	v_pk_fma_f32 v[0:1], v[4:5], v[14:15], v[24:25]
	v_pk_fma_f32 v[2:3], v[6:7], v[12:13], v[26:27]
	v_bfe_u32 v4, v10, 16, 1
	v_bfe_u32 v6, v8, 16, 1
	v_bfe_u32 v5, v11, 16, 1
	v_bfe_u32 v7, v9, 16, 1
	v_add3_u32 v4, v10, v4, s45
	v_add3_u32 v6, v8, v6, s45
	v_add3_u32 v5, v11, v5, s45
	v_add3_u32 v7, v9, v7, s45
	v_lshrrev_b32_e32 v4, 16, v4
	v_lshrrev_b32_e32 v6, 16, v6
	v_and_or_b32 v4, v5, s56, v4
	v_and_or_b32 v5, v7, s56, v6
	global_store_dwordx2 v[40:41], v[4:5], off offset:1536

; template <int MODE> __device__ __forceinline__ void norm_row2(const float* xa, const float* xb, const float* nw, const float* sca, const float* sha, const float* scb, const float* shb, ...
;     const f32x4* pa = (const f32x4*)xa + lane; const f32x4* pb = (const f32x4*)xb + lane;
;     f32x4 va[4], vb[4]; float s0 = 0.f, s1 = 0.f;
; #pragma unroll
;     for (int j = 0; j < 4; ++j) { va[j] = pa[64 * j]; vb[j] = pb[64 * j]; }
; #pragma unroll
;     for (int j = 0; j < 4; ++j) { s0 += (va[j].x * va[j].x + va[j].y * va[j].y) + (va[j].z * va[j].z + va[j].w * va[j].w); s1 += (vb[j].x * vb[j].x + vb[j].y * vb[j].y) + (vb[j].z * vb[j].z + vb[j].w * vb[j].w); }
; #pragma unroll
;     for (int o = 1; o < 64; o <<= 1) { s0 += __shfl_xor(s0, o); s1 += __shfl_xor(s1, o); }
;     const float r0 = 1.f / sqrtf(s0 * (1.f / D) + eps), r1 = 1.f / sqrtf(s1 * (1.f / D) + eps);
; __global__ void __launch_bounds__(512, 2) hymba_fwd(Args a) {
;     ...
;         for (int row = gw; row < TT; row += 2 * NGW) { const int rb_ = row + NGW; const int mb = batch_of_row(row);
;             if (rb_ < TT) { const int mb2 = batch_of_row(rb_);
;                 norm_row2<0>(a.out + (size_t)row * D, a.out + (size_t)rb_ * D, a.in[26], MOD + mb * 6144 + 4096, MOD + mb * 6144 + 3072, MOD + mb2 * 6144 + 4096, MOD + mb2 * 6144 + 3072, XN + (size_t)row * D, XN + (size_t)rb_ * D, nullptr, nullptr, 1e-6f, lane); }
.LBB0_1157:
	s_andn2_b64 vcc, exec, s[0:1]
	s_mov_b64 s[26:27], s[12:13]
	s_cbranch_vccnz .LBB0_1154
	global_load_dwordx4 v[24:27], v[12:13], off nt
	global_load_dwordx4 v[16:19], v[12:13], off offset:1024 nt
	global_load_dwordx4 v[0:3], v[12:13], off offset:3072 nt
	global_load_dwordx4 v[8:11], v[12:13], off offset:2048 nt
	v_lshl_add_u64 v[12:13], s[22:23], 0, v[164:165]
	global_load_dwordx4 v[28:31], v[12:13], off nt
	global_load_dwordx4 v[20:23], v[12:13], off offset:1024 nt
	global_load_dwordx4 v[4:7], v[12:13], off offset:3072 nt
	s_nop 0
	global_load_dwordx4 v[12:15], v[12:13], off offset:2048 nt
	v_cmp_lt_i32_e32 vcc, v42, v41
	s_add_i32 s1, s2, 0xffff8000
	s_lshr_b32 s1, s1, 11
	v_cndmask_b32_e32 v52, v40, v42, vcc
	v_cmp_lt_i32_e32 vcc, v43, v41
	v_lshlrev_b32_e32 v73, 2, v52
	s_ashr_i32 s0, s2, 14
	v_cndmask_b32_e32 v53, v40, v43, vcc
	v_cmp_lt_i32_e32 vcc, v44, v41
	v_lshlrev_b32_e32 v75, 2, v53
	s_add_i32 s1, s1, 2
	v_cndmask_b32_e32 v54, v40, v44, vcc
	v_cmp_lt_i32_e32 vcc, v45, v41
	v_lshlrev_b32_e32 v76, 2, v54
	s_cmp_lt_i32 s2, 0x8000
	v_cndmask_b32_e32 v55, v40, v45, vcc
	v_lshlrev_b32_e32 v77, 2, v55
	v_cmp_lt_i32_e32 vcc, v46, v41
	s_cselect_b32 s36, s0, s1
	s_ashr_i32 s3, s2, 31
	s_ashr_i32 s25, s24, 31
	s_lshl_b64 s[26:27], s[2:3], 10
	s_lshl_b64 s[0:1], s[24:25], 2
	s_add_u32 s0, s34, s0
	s_addc_u32 s1, s35, s1
	s_mul_i32 s2, s36, 0x1800
	s_add_u32 s36, s0, 0x4000
	s_addc_u32 s37, s1, 0
	s_add_u32 s24, s0, 0x3000
	s_addc_u32 s25, s1, 0
	s_ashr_i32 s3, s2, 31
	s_lshl_b64 s[0:1], s[2:3], 2
	s_add_u32 s0, s34, s0
	s_addc_u32 s1, s35, s1
	s_add_u32 s40, s0, 0x4000
	s_addc_u32 s41, s1, 0
	s_add_u32 s42, s0, 0x3000
	s_addc_u32 s43, s1, 0
	s_waitcnt vmcnt(0)
	v_pk_mul_f32 v[52:53], v[26:27], v[26:27]
	v_pk_mul_f32 v[54:55], v[24:25], v[24:25]
	v_pk_mul_f32 v[56:57], v[18:19], v[18:19]
	v_pk_mul_f32 v[58:59], v[16:17], v[16:17]
	v_pk_mov_b32 v[64:65], v[54:55], v[52:53] op_sel:[1,0]
	v_mov_b32_e32 v55, v53
	v_pk_mul_f32 v[52:53], v[30:31], v[30:31]
	v_pk_mul_f32 v[66:67], v[28:29], v[28:29]
	v_pk_mov_b32 v[68:69], v[58:59], v[56:57] op_sel:[1,0]
	v_mov_b32_e32 v59, v57
	v_mul_f32_e32 v60, v9, v9
	v_mul_f32_e32 v62, v11, v11
	v_pk_add_f32 v[54:55], v[64:65], v[54:55]
	v_pk_mov_b32 v[64:65], v[66:67], v[52:53] op_sel:[1,0]
	v_mov_b32_e32 v67, v53
	v_pk_add_f32 v[52:53], v[68:69], v[58:59]
	v_mul_f32_e32 v78, v0, v0
	v_mul_f32_e32 v79, v1, v1
	v_mul_f32_e32 v80, v2, v2
	v_mul_f32_e32 v81, v3, v3
	v_pk_fma_f32 v[60:61], v[8:9], v[8:9], v[60:61] op_sel_hi:[1,1,0]
	v_pk_fma_f32 v[62:63], v[10:11], v[10:11], v[62:63] op_sel_hi:[1,1,0]
	v_pk_add_f32 v[54:55], v[54:55], v[54:55] op_sel:[0,1] op_sel_hi:[1,0]
	v_pk_add_f32 v[52:53], v[52:53], v[52:53] op_sel:[0,1] op_sel_hi:[1,0]
	v_mov_b32_e32 v61, v80
	v_mov_b32_e32 v63, v81
	v_mov_b32_e32 v55, v78
	v_mov_b32_e32 v53, v79
	v_pk_add_f32 v[60:61], v[60:61], v[62:63]
	v_pk_add_f32 v[52:53], v[54:55], v[52:53]
	v_pk_mul_f32 v[56:57], v[22:23], v[22:23]
	v_pk_add_f32 v[52:53], v[52:53], v[60:61]
	v_pk_mul_f32 v[70:71], v[20:21], v[20:21]
	v_add_f32_e32 v60, v52, v53
	ds_bpermute_b32 v61, v73, v60
	v_mul_f32_e32 v72, v13, v13
	v_mul_f32_e32 v74, v15, v15
	v_mul_f32_e32 v84, v6, v6
	v_mul_f32_e32 v85, v7, v7
	v_pk_mov_b32 v[58:59], v[70:71], v[56:57] op_sel:[1,0]
	v_mov_b32_e32 v71, v57
	v_pk_fma_f32 v[56:57], v[12:13], v[12:13], v[72:73] op_sel_hi:[1,1,0]
	v_pk_fma_f32 v[68:69], v[14:15], v[14:15], v[74:75] op_sel_hi:[1,1,0]
	v_mov_b32_e32 v57, v84
	v_mov_b32_e32 v69, v85
	v_pk_add_f32 v[54:55], v[56:57], v[68:69]
	s_waitcnt lgkmcnt(0)
	v_add_f32_e32 v56, v60, v61
	v_pk_add_f32 v[64:65], v[64:65], v[66:67]
	v_pk_add_f32 v[58:59], v[58:59], v[70:71]
	ds_bpermute_b32 v57, v75, v56
	v_mul_f32_e32 v82, v4, v4
	v_mul_f32_e32 v83, v5, v5
	v_pk_add_f32 v[62:63], v[64:65], v[64:65] op_sel:[0,1] op_sel_hi:[1,0]
	v_pk_add_f32 v[52:53], v[58:59], v[58:59] op_sel:[0,1] op_sel_hi:[1,0]
	v_mov_b32_e32 v63, v82
	v_mov_b32_e32 v53, v83
	v_pk_add_f32 v[52:53], v[62:63], v[52:53]
	s_nop 0
	v_pk_add_f32 v[52:53], v[52:53], v[54:55]
	s_waitcnt lgkmcnt(0)
	v_add_f32_e32 v54, v56, v57
	v_add_f32_e32 v52, v52, v53
	ds_bpermute_b32 v53, v73, v52
	ds_bpermute_b32 v55, v76, v54
	s_waitcnt lgkmcnt(1)
	v_add_f32_e32 v52, v52, v53
	s_waitcnt lgkmcnt(0)
	v_add_f32_e32 v54, v54, v55
	ds_bpermute_b32 v53, v75, v52
	ds_bpermute_b32 v55, v77, v54
	s_waitcnt lgkmcnt(1)
	v_add_f32_e32 v52, v52, v53
	s_waitcnt lgkmcnt(0)
	v_add_f32_e32 v54, v54, v55
	v_cndmask_b32_e32 v55, v40, v46, vcc
	ds_bpermute_b32 v53, v76, v52
	v_lshlrev_b32_e32 v56, 2, v55
	ds_bpermute_b32 v55, v56, v54
	v_cmp_lt_i32_e32 vcc, v47, v41
	s_waitcnt lgkmcnt(1)
	v_add_f32_e32 v57, v52, v53
	v_cndmask_b32_e32 v52, v40, v47, vcc
	ds_bpermute_b32 v58, v77, v57
	s_waitcnt lgkmcnt(1)
	v_add_f32_e32 v59, v54, v55
	v_lshlrev_b32_e32 v72, 2, v52
	ds_bpermute_b32 v60, v72, v59
	global_load_dwordx4 v[52:55], v[32:33], off
	s_waitcnt lgkmcnt(1)
	v_add_f32_e32 v73, v57, v58
	ds_bpermute_b32 v74, v56, v73
	s_waitcnt lgkmcnt(1)
	v_add_f32_e32 v60, v59, v60
	global_load_dwordx4 v[56:59], v48, s[36:37]
	v_fmamk_f32 v75, v60, 0x3a800000, v38
	global_load_dwordx4 v[60:63], v48, s[24:25]
	global_load_dwordx4 v[64:67], v48, s[40:41]
	global_load_dwordx4 v[68:71], v48, s[42:43]
	v_mul_f32_e32 v76, 0x4f800000, v75
	v_cmp_gt_f32_e32 vcc, s7, v75
	s_waitcnt lgkmcnt(0)
	v_add_f32_e32 v73, v73, v74
	ds_bpermute_b32 v72, v72, v73
	v_cndmask_b32_e32 v75, v75, v76, vcc
	v_sqrt_f32_e32 v76, v75
	s_waitcnt lgkmcnt(0)
; __device__ __forceinline__ unsigned pk2(float lo, float hi) { return f2bf(lo) | (f2bf(hi) << 16); }
; template <int MODE> __device__ __forceinline__ void norm_row2(const float* xa, const float* xb, const float* nw, const float* sca, const float* sha, const float* scb, const float* shb, ...
;     ...
;     const float r0 = 1.f / sqrtf(s0 * (1.f / D) + eps), r1 = 1.f / sqrtf(s1 * (1.f / D) + eps);
; #pragma unroll
;     for (int j = 0; j < 4; ++j) { const f32x4 w = ((const f32x4*)nw)[64 * j + lane]; f32x4 ya = va[j] * r0 * w, yb = vb[j] * r1 * w;
;         if (MODE == 0) { const f32x4 ca = ((const f32x4*)sca)[64 * j + lane], ha = ((const f32x4*)sha)[64 * j + lane], cb = ((const f32x4*)scb)[64 * j + lane], hb = ((const f32x4*)shb)[64 * j + lane];
;             ya = ya * (ca + 1.f) + ha; yb = yb * (cb + 1.f) + hb;
;             u32x2 o; o.x = pk2(ya.x, ya.y); o.y = pk2(ya.z, ya.w); ((u32x2*)oa)[64 * j + lane] = o; o.x = pk2(yb.x, yb.y); o.y = pk2(yb.z, yb.w); ((u32x2*)ob)[64 * j + lane] = o; }
	v_add_f32_e32 v72, v73, v72
	v_add_u32_e32 v74, -1, v76
	v_fma_f32 v77, -v74, v76, v75
	v_cmp_ge_f32_e64 s[0:1], 0, v77
	v_add_u32_e32 v77, 1, v76
	v_fmamk_f32 v72, v72, 0x3a800000, v38
	v_cndmask_b32_e64 v74, v76, v74, s[0:1]
	v_fma_f32 v76, -v77, v76, v75
	v_cmp_lt_f32_e64 s[0:1], 0, v76
	v_mul_f32_e32 v78, 0x4f800000, v72
	s_nop 0
	v_cndmask_b32_e64 v74, v74, v77, s[0:1]
	v_mul_f32_e32 v76, 0x37800000, v74
	v_cndmask_b32_e32 v74, v74, v76, vcc
	v_cmp_class_f32_e32 vcc, v75, v39
	s_nop 1
	v_cndmask_b32_e32 v74, v74, v75, vcc
	v_div_scale_f32 v75, s[0:1], v74, v74, 1.0
	v_rcp_f32_e32 v76, v75
	v_cmp_gt_f32_e64 s[0:1], s7, v72
	v_fma_f32 v73, -v75, v76, 1.0
	s_nop 0
	v_cndmask_b32_e64 v72, v72, v78, s[0:1]
	v_fmac_f32_e32 v76, v73, v76
	v_div_scale_f32 v73, vcc, 1.0, v74, 1.0
	v_sqrt_f32_e32 v78, v72
	v_mul_f32_e32 v77, v73, v76
	v_fma_f32 v79, -v75, v77, v73
	v_fmac_f32_e32 v77, v79, v76
	v_fma_f32 v73, -v75, v77, v73
	v_add_u32_e32 v75, -1, v78
	v_fma_f32 v79, -v75, v78, v72
	v_cmp_ge_f32_e64 s[2:3], 0, v79
	v_add_u32_e32 v79, 1, v78
	s_nop 0
	v_cndmask_b32_e64 v75, v78, v75, s[2:3]
	v_fma_f32 v78, -v79, v78, v72
	v_cmp_lt_f32_e64 s[2:3], 0, v78
	s_nop 1
	v_cndmask_b32_e64 v75, v75, v79, s[2:3]
	v_mul_f32_e32 v78, 0x37800000, v75
	v_cndmask_b32_e64 v75, v75, v78, s[0:1]
	v_cmp_class_f32_e64 s[0:1], v72, v39
	s_nop 1
	v_cndmask_b32_e64 v75, v75, v72, s[0:1]
	v_div_scale_f32 v78, s[0:1], v75, v75, 1.0
	v_rcp_f32_e32 v79, v78
	v_div_fmas_f32 v72, v73, v76, v77
	v_div_fixup_f32 v72, v72, v74, 1.0
	v_fma_f32 v73, -v78, v79, 1.0
	v_fmac_f32_e32 v79, v73, v79
	v_div_scale_f32 v73, vcc, 1.0, v75, 1.0
	v_mul_f32_e32 v74, v73, v79
	v_fma_f32 v76, -v78, v74, v73
	v_fmac_f32_e32 v74, v76, v79
	v_fma_f32 v73, -v78, v74, v73
	v_div_fmas_f32 v73, v73, v79, v74
	v_div_fixup_f32 v74, v73, v75, 1.0
	v_pk_mul_f32 v[26:27], v[26:27], v[72:73] op_sel_hi:[1,0]
	v_pk_mul_f32 v[24:25], v[24:25], v[72:73] op_sel_hi:[1,0]
	v_pk_mul_f32 v[30:31], v[30:31], v[74:75] op_sel_hi:[1,0]
	v_pk_mul_f32 v[28:29], v[28:29], v[74:75] op_sel_hi:[1,0]
	s_waitcnt vmcnt(4)
	v_pk_mul_f32 v[24:25], v[52:53], v[24:25]
	v_pk_mul_f32 v[26:27], v[54:55], v[26:27]
	v_pk_mul_f32 v[28:29], v[52:53], v[28:29]
	v_pk_mul_f32 v[30:31], v[54:55], v[30:31]
	s_waitcnt vmcnt(3)
	v_pk_add_f32 v[52:53], v[58:59], 1.0 op_sel_hi:[1,0]
	v_pk_add_f32 v[54:55], v[56:57], 1.0 op_sel_hi:[1,0]
	s_waitcnt vmcnt(2)
	v_pk_fma_f32 v[26:27], v[52:53], v[26:27], v[62:63]
	v_pk_fma_f32 v[24:25], v[54:55], v[24:25], v[60:61]
	s_waitcnt vmcnt(1)
	v_pk_add_f32 v[52:53], v[66:67], 1.0 op_sel_hi:[1,0]
	v_pk_add_f32 v[54:55], v[64:65], 1.0 op_sel_hi:[1,0]
	s_waitcnt vmcnt(0)
	v_pk_fma_f32 v[30:31], v[52:53], v[30:31], v[70:71]
	v_bfe_u32 v52, v24, 16, 1
	v_add3_u32 v24, v24, v52, s44
	v_bfe_u32 v52, v25, 16, 1
	v_lshrrev_b32_e32 v24, 16, v24
	v_add3_u32 v25, v25, v52, s44
	v_and_or_b32 v24, v25, s45, v24
	v_bfe_u32 v25, v26, 16, 1
	v_add3_u32 v25, v26, v25, s44
	v_bfe_u32 v26, v27, 16, 1
	v_lshrrev_b32_e32 v25, 16, v25
	v_add3_u32 v26, v27, v26, s44
	v_add_co_u32_e32 v36, vcc, s52, v36
	v_pk_fma_f32 v[28:29], v[54:55], v[28:29], v[68:69]
	v_and_or_b32 v25, v26, s45, v25
	v_addc_co_u32_e32 v37, vcc, 0, v37, vcc
	global_store_dwordx2 v[36:37], v[24:25], off
	v_bfe_u32 v24, v28, 16, 1
	v_add3_u32 v24, v28, v24, s44
	v_bfe_u32 v25, v29, 16, 1
	v_lshrrev_b32_e32 v24, 16, v24
	v_add3_u32 v25, v29, v25, s44
	v_and_or_b32 v24, v25, s45, v24
	v_bfe_u32 v25, v30, 16, 1
	v_add3_u32 v25, v30, v25, s44
	v_bfe_u32 v26, v31, 16, 1
	v_lshrrev_b32_e32 v25, 16, v25
	v_add3_u32 v26, v31, v26, s44
	v_and_or_b32 v25, v26, s45, v25
	v_lshl_add_u64 v[26:27], s[20:21], 0, v[166:167]
	v_add_co_u32_e32 v64, vcc, s52, v26
	v_pk_mul_f32 v[18:19], v[18:19], v[72:73] op_sel_hi:[1,0]
	s_nop 0
	v_addc_co_u32_e32 v65, vcc, 0, v27, vcc
	global_store_dwordx2 v[64:65], v[24:25], off
	global_load_dwordx4 v[24:27], v[32:33], off offset:1024
	s_nop 0
	global_load_dwordx4 v[28:31], v49, s[36:37]
	global_load_dwordx4 v[52:55], v49, s[24:25]
	global_load_dwordx4 v[56:59], v49, s[40:41]
	global_load_dwordx4 v[60:63], v49, s[42:43]
	v_pk_mul_f32 v[16:17], v[16:17], v[72:73] op_sel_hi:[1,0]
	v_pk_mul_f32 v[22:23], v[22:23], v[74:75] op_sel_hi:[1,0]
	v_pk_mul_f32 v[20:21], v[20:21], v[74:75] op_sel_hi:[1,0]
	v_pk_mul_f32 v[10:11], v[10:11], v[72:73] op_sel_hi:[1,0]
	v_pk_mul_f32 v[8:9], v[8:9], v[72:73] op_sel_hi:[1,0]
	v_pk_mul_f32 v[14:15], v[14:15], v[74:75] op_sel_hi:[1,0]
	v_pk_mul_f32 v[12:13], v[12:13], v[74:75] op_sel_hi:[1,0]
	v_pk_mul_f32 v[2:3], v[2:3], v[72:73] op_sel_hi:[1,0]
	v_pk_mul_f32 v[0:1], v[0:1], v[72:73] op_sel_hi:[1,0]
	v_pk_mul_f32 v[4:5], v[4:5], v[74:75] op_sel_hi:[1,0]
	v_pk_mul_f32 v[6:7], v[6:7], v[74:75] op_sel_hi:[1,0]
	s_waitcnt vmcnt(4)
; __device__ __forceinline__ unsigned pk2(float lo, float hi) { return f2bf(lo) | (f2bf(hi) << 16); }
; template <int MODE> __device__ __forceinline__ void norm_row2(const float* xa, const float* xb, const float* nw, const float* sca, const float* sha, const float* scb, const float* shb, ...
;     ...
;     for (int j = 0; j < 4; ++j) { const f32x4 w = ((const f32x4*)nw)[64 * j + lane]; f32x4 ya = va[j] * r0 * w, yb = vb[j] * r1 * w;
;         if (MODE == 0) { const f32x4 ca = ((const f32x4*)sca)[64 * j + lane], ha = ((const f32x4*)sha)[64 * j + lane], cb = ((const f32x4*)scb)[64 * j + lane], hb = ((const f32x4*)shb)[64 * j + lane];
;             ya = ya * (ca + 1.f) + ha; yb = yb * (cb + 1.f) + hb;
;             u32x2 o; o.x = pk2(ya.x, ya.y); o.y = pk2(ya.z, ya.w); ((u32x2*)oa)[64 * j + lane] = o; o.x = pk2(yb.x, yb.y); o.y = pk2(yb.z, yb.w); ((u32x2*)ob)[64 * j + lane] = o; }
	v_pk_mul_f32 v[16:17], v[16:17], v[24:25]
	v_pk_mul_f32 v[18:19], v[18:19], v[26:27]
	v_pk_mul_f32 v[20:21], v[24:25], v[20:21]
	v_pk_mul_f32 v[22:23], v[26:27], v[22:23]
	s_waitcnt vmcnt(3)
	v_pk_add_f32 v[24:25], v[30:31], 1.0 op_sel_hi:[1,0]
	v_pk_add_f32 v[26:27], v[28:29], 1.0 op_sel_hi:[1,0]
	s_waitcnt vmcnt(2)
	v_pk_fma_f32 v[18:19], v[18:19], v[24:25], v[54:55]
	v_pk_fma_f32 v[16:17], v[16:17], v[26:27], v[52:53]
	s_waitcnt vmcnt(1)
	v_pk_add_f32 v[24:25], v[58:59], 1.0 op_sel_hi:[1,0]
	v_pk_add_f32 v[26:27], v[56:57], 1.0 op_sel_hi:[1,0]
	s_waitcnt vmcnt(0)
	v_pk_fma_f32 v[22:23], v[22:23], v[24:25], v[62:63]
	v_bfe_u32 v24, v16, 16, 1
	v_add3_u32 v16, v16, v24, s44
	v_bfe_u32 v24, v17, 16, 1
	v_lshrrev_b32_e32 v16, 16, v16
	v_add3_u32 v17, v17, v24, s44
	v_and_or_b32 v16, v17, s45, v16
	v_bfe_u32 v17, v18, 16, 1
	v_add3_u32 v17, v18, v17, s44
	v_bfe_u32 v18, v19, 16, 1
	v_lshrrev_b32_e32 v17, 16, v17
	v_add3_u32 v18, v19, v18, s44
	v_pk_fma_f32 v[20:21], v[20:21], v[26:27], v[60:61]
	v_and_or_b32 v17, v18, s45, v17
	global_store_dwordx2 v[36:37], v[16:17], off offset:512
	v_bfe_u32 v16, v20, 16, 1
	v_add3_u32 v16, v20, v16, s44
	v_bfe_u32 v17, v21, 16, 1
	v_lshrrev_b32_e32 v16, 16, v16
	v_add3_u32 v17, v21, v17, s44
	v_and_or_b32 v16, v17, s45, v16
	v_bfe_u32 v17, v22, 16, 1
	v_add3_u32 v17, v22, v17, s44
	v_bfe_u32 v18, v23, 16, 1
	v_lshrrev_b32_e32 v17, 16, v17
	v_add3_u32 v18, v23, v18, s44
	v_and_or_b32 v17, v18, s45, v17
	global_store_dwordx2 v[64:65], v[16:17], off offset:512
	global_load_dwordx4 v[16:19], v[32:33], off offset:2048
	s_nop 0
	global_load_dwordx4 v[20:23], v50, s[36:37]
	global_load_dwordx4 v[24:27], v50, s[40:41]
	global_load_dwordx4 v[28:31], v50, s[24:25]
	global_load_dwordx4 v[52:55], v50, s[42:43]
	s_waitcnt vmcnt(4)
	v_pk_mul_f32 v[8:9], v[8:9], v[16:17]
	v_pk_mul_f32 v[10:11], v[10:11], v[18:19]
	v_pk_mul_f32 v[12:13], v[12:13], v[16:17]
	v_pk_mul_f32 v[14:15], v[14:15], v[18:19]
	s_waitcnt vmcnt(3)
	v_pk_add_f32 v[16:17], v[22:23], 1.0 op_sel_hi:[1,0]
	v_pk_add_f32 v[18:19], v[20:21], 1.0 op_sel_hi:[1,0]
	s_waitcnt vmcnt(1)
	v_pk_fma_f32 v[10:11], v[10:11], v[16:17], v[30:31]
	v_pk_fma_f32 v[8:9], v[8:9], v[18:19], v[28:29]
	v_bfe_u32 v18, v10, 16, 1
	v_bfe_u32 v16, v8, 16, 1
	v_bfe_u32 v17, v9, 16, 1
	v_bfe_u32 v19, v11, 16, 1
	v_add3_u32 v8, v8, v16, s44
	v_add3_u32 v10, v10, v18, s44
	v_pk_add_f32 v[20:21], v[26:27], 1.0 op_sel_hi:[1,0]
	v_pk_add_f32 v[22:23], v[24:25], 1.0 op_sel_hi:[1,0]
	v_add3_u32 v9, v9, v17, s44
	v_add3_u32 v11, v11, v19, s44
	v_lshrrev_b32_e32 v8, 16, v8
	v_lshrrev_b32_e32 v10, 16, v10
	s_waitcnt vmcnt(0)
	v_pk_fma_f32 v[14:15], v[14:15], v[20:21], v[54:55]
	v_pk_fma_f32 v[12:13], v[12:13], v[22:23], v[52:53]
	v_and_or_b32 v8, v9, s45, v8
	v_and_or_b32 v9, v11, s45, v10
	v_bfe_u32 v20, v12, 16, 1
	global_store_dwordx2 v[36:37], v[8:9], off offset:1024
	v_bfe_u32 v9, v14, 16, 1
	v_add3_u32 v12, v12, v20, s44
	v_bfe_u32 v8, v13, 16, 1
	v_add3_u32 v9, v14, v9, s44
	v_bfe_u32 v10, v15, 16, 1
	v_lshrrev_b32_e32 v12, 16, v12
	v_add3_u32 v8, v13, v8, s44
	v_lshrrev_b32_e32 v9, 16, v9
	v_add3_u32 v10, v15, v10, s44
	v_and_or_b32 v8, v8, s45, v12
	v_and_or_b32 v9, v10, s45, v9
	global_store_dwordx2 v[64:65], v[8:9], off offset:1024
	global_load_dwordx4 v[8:11], v[32:33], off offset:3072
	s_nop 0
	global_load_dwordx4 v[12:15], v51, s[36:37]
	global_load_dwordx4 v[16:19], v51, s[40:41]
	global_load_dwordx4 v[20:23], v51, s[24:25]
	global_load_dwordx4 v[24:27], v51, s[42:43]
	s_waitcnt vmcnt(4)
	v_pk_mul_f32 v[0:1], v[0:1], v[8:9]
	v_pk_mul_f32 v[2:3], v[2:3], v[10:11]
	v_pk_mul_f32 v[6:7], v[6:7], v[10:11]
	v_pk_mul_f32 v[4:5], v[4:5], v[8:9]
	s_waitcnt vmcnt(3)
	v_pk_add_f32 v[8:9], v[14:15], 1.0 op_sel_hi:[1,0]
	v_pk_add_f32 v[10:11], v[12:13], 1.0 op_sel_hi:[1,0]
	s_waitcnt vmcnt(2)
	v_pk_add_f32 v[12:13], v[18:19], 1.0 op_sel_hi:[1,0]
	v_pk_add_f32 v[14:15], v[16:17], 1.0 op_sel_hi:[1,0]
	s_waitcnt vmcnt(1)
	v_pk_fma_f32 v[8:9], v[2:3], v[8:9], v[22:23]
	v_pk_fma_f32 v[10:11], v[0:1], v[10:11], v[20:21]
	s_waitcnt vmcnt(0)
	v_pk_fma_f32 v[0:1], v[4:5], v[14:15], v[24:25]
	v_pk_fma_f32 v[2:3], v[6:7], v[12:13], v[26:27]
	v_bfe_u32 v4, v10, 16, 1
	v_bfe_u32 v6, v8, 16, 1
	v_bfe_u32 v5, v11, 16, 1
	v_bfe_u32 v7, v9, 16, 1
	v_add3_u32 v4, v10, v4, s44
	v_add3_u32 v6, v8, v6, s44
	v_add3_u32 v5, v11, v5, s44
	v_add3_u32 v7, v9, v7, s44
	v_lshrrev_b32_e32 v4, 16, v4
	v_lshrrev_b32_e32 v6, 16, v6
	v_and_or_b32 v4, v5, s45, v4
	v_and_or_b32 v5, v7, s45, v6
	global_store_dwordx2 v[36:37], v[4:5], off offset:1536
	s_branch .LBB0_1154

; template <int MODE> __device__ __forceinline__ void norm_row2(const float* xa, const float* xb, const float* nw, const float* sca, const float* sha, const float* scb, const float* shb, ...
;     ...
;         else { ((f32x4*)fa_)[64 * j + lane] = ya; ((f32x4*)fb_)[64 * j + lane] = yb; } }
; __global__ void __launch_bounds__(512, 2) hymba_fwd(Args a) {
;     ...
;         for (int row = gw; row < TT; row += 2 * NGW) { const int rb_ = row + NGW;
;             if (rb_ < TT) norm_row2<1>(a.out + (size_t)row * D, a.out + (size_t)rb_ * D, a.in[29], nullptr, nullptr, nullptr, nullptr, nullptr, nullptr, a.out + (size_t)row * D, a.out + (size_t)rb_ * D, 1e-6f, lane);
;             else norm_row<1>(a.out + (size_t)row * D, a.in[29], nullptr, nullptr, nullptr, a.out + (size_t)row * D, 1e-6f, lane); }
.LBB0_1237:
	s_add_i32 s0, s4, s92
	v_lshl_add_u64 v[4:5], v[34:35], 0, s[8:9]
	s_cmp_lt_i32 s0, 0x18000
	s_waitcnt lgkmcnt(0)
	global_store_dwordx4 v[4:5], v[0:3], off offset:3072 nt
	s_cbranch_scc0 .LBB0_1242

; template <int MODE> __device__ __forceinline__ void norm_row2(const float* xa, const float* xb, const float* nw, const float* sca, const float* sha, const float* scb, const float* shb, ...
;     const f32x4* pa = (const f32x4*)xa + lane; const f32x4* pb = (const f32x4*)xb + lane;
;     f32x4 va[4], vb[4]; float s0 = 0.f, s1 = 0.f;
; #pragma unroll
;     for (int j = 0; j < 4; ++j) { va[j] = pa[64 * j]; vb[j] = pb[64 * j]; }
; #pragma unroll
;     for (int j = 0; j < 4; ++j) { s0 += (va[j].x * va[j].x + va[j].y * va[j].y) + (va[j].z * va[j].z + va[j].w * va[j].w); s1 += (vb[j].x * vb[j].x + vb[j].y * vb[j].y) + (vb[j].z * vb[j].z + vb[j].w * vb[j].w); }
; #pragma unroll
;     for (int o = 1; o < 64; o <<= 1) { s0 += __shfl_xor(s0, o); s1 += __shfl_xor(s1, o); }
;     const float r0 = 1.f / sqrtf(s0 * (1.f / D) + eps), r1 = 1.f / sqrtf(s1 * (1.f / D) + eps);
; __global__ void __launch_bounds__(512, 2) hymba_fwd(Args a) {
;     ...
;         for (int row = gw; row < TT; row += 2 * NGW) { const int rb_ = row + NGW;
;             if (rb_ < TT) norm_row2<1>(a.out + (size_t)row * D, a.out + (size_t)rb_ * D, a.in[29], nullptr, nullptr, nullptr, nullptr, nullptr, nullptr, a.out + (size_t)row * D, a.out + (size_t)rb_ * D, 1e-6f, lane);
.LBB0_1240:
	s_andn2_b64 vcc, exec, s[0:1]
	s_cbranch_vccnz .LBB0_1237
	global_load_dwordx4 v[24:27], v40, s[6:7] nt
	global_load_dwordx4 v[16:19], v40, s[6:7] offset:1024 nt
	global_load_dwordx4 v[4:7], v40, s[6:7] offset:3072 nt
	global_load_dwordx4 v[8:11], v40, s[6:7] offset:2048 nt
	s_ashr_i32 s5, s4, 31
	s_lshl_b64 s[8:9], s[4:5], 12
	v_lshl_add_u64 v[36:37], v[34:35], 0, s[8:9]
	global_load_dwordx4 v[28:31], v[36:37], off nt
	global_load_dwordx4 v[20:23], v[36:37], off offset:1024 nt
	s_waitcnt lgkmcnt(0)
	global_load_dwordx4 v[0:3], v[36:37], off offset:3072 nt
	global_load_dwordx4 v[12:15], v[36:37], off offset:2048 nt
	v_cmp_lt_i32_e32 vcc, v43, v42
	s_waitcnt vmcnt(0)
	v_pk_mul_f32 v[52:53], v[24:25], v[24:25]
	v_cndmask_b32_e32 v49, v41, v43, vcc
	v_cmp_lt_i32_e32 vcc, v44, v42
	v_pk_mul_f32 v[54:55], v[18:19], v[18:19]
	v_pk_mul_f32 v[56:57], v[16:17], v[16:17]
	v_cndmask_b32_e32 v50, v41, v44, vcc
	v_lshlrev_b32_e32 v70, 2, v50
	v_pk_mul_f32 v[50:51], v[26:27], v[26:27]
	v_mul_f32_e32 v61, v6, v6
	v_mul_f32_e32 v58, v9, v9
	v_mul_f32_e32 v60, v11, v11
	v_pk_mov_b32 v[62:63], v[52:53], v[50:51] op_sel:[1,0]
	v_mov_b32_e32 v53, v51
	v_pk_mov_b32 v[50:51], v[56:57], v[54:55] op_sel:[1,0]
	v_mov_b32_e32 v57, v55
	v_mul_f32_e32 v64, v7, v7
	v_pk_fma_f32 v[54:55], v[8:9], v[8:9], v[58:59] op_sel_hi:[1,1,0]
	v_pk_fma_f32 v[58:59], v[10:11], v[10:11], v[60:61] op_sel_hi:[1,1,0]
	v_pk_add_f32 v[52:53], v[62:63], v[52:53]
	v_pk_add_f32 v[50:51], v[50:51], v[56:57]
	v_cmp_lt_i32_e32 vcc, v45, v42
	v_mul_f32_e32 v71, v4, v4
	v_mul_f32_e32 v72, v5, v5
	v_mov_b32_e32 v55, v61
	v_mov_b32_e32 v59, v64
	v_pk_add_f32 v[52:53], v[52:53], v[52:53] op_sel:[0,1] op_sel_hi:[1,0]
	v_pk_add_f32 v[50:51], v[50:51], v[50:51] op_sel:[0,1] op_sel_hi:[1,0]
	v_cndmask_b32_e32 v67, v41, v45, vcc
	v_pk_mul_f32 v[56:57], v[30:31], v[30:31]
	v_pk_mul_f32 v[60:61], v[28:29], v[28:29]
	v_pk_mul_f32 v[62:63], v[22:23], v[22:23]
	v_pk_mul_f32 v[64:65], v[20:21], v[20:21]
	v_pk_add_f32 v[54:55], v[54:55], v[58:59]
	v_mul_f32_e32 v58, v13, v13
	v_mul_f32_e32 v66, v15, v15
	v_mov_b32_e32 v53, v71
	v_mov_b32_e32 v51, v72
	v_mul_f32_e32 v75, v2, v2
	v_mul_f32_e32 v76, v3, v3
	v_pk_mov_b32 v[68:69], v[60:61], v[56:57] op_sel:[1,0]
	v_mov_b32_e32 v61, v57
	v_pk_mov_b32 v[56:57], v[64:65], v[62:63] op_sel:[1,0]
	v_mov_b32_e32 v65, v63
	v_pk_fma_f32 v[58:59], v[12:13], v[12:13], v[58:59] op_sel_hi:[1,1,0]
	v_pk_fma_f32 v[62:63], v[14:15], v[14:15], v[66:67] op_sel_hi:[1,1,0]
	v_pk_add_f32 v[50:51], v[52:53], v[50:51]
	v_pk_add_f32 v[56:57], v[56:57], v[64:65]
	v_mov_b32_e32 v59, v75
	v_mov_b32_e32 v63, v76
	v_pk_add_f32 v[50:51], v[50:51], v[54:55]
	v_lshlrev_b32_e32 v49, 2, v49
	v_pk_add_f32 v[54:55], v[56:57], v[56:57] op_sel:[0,1] op_sel_hi:[1,0]
	v_pk_add_f32 v[56:57], v[58:59], v[62:63]
	v_add_f32_e32 v58, v50, v51
	v_pk_add_f32 v[60:61], v[68:69], v[60:61]
	ds_bpermute_b32 v59, v49, v58
	v_mul_f32_e32 v73, v0, v0
	v_mul_f32_e32 v74, v1, v1
	v_pk_add_f32 v[52:53], v[60:61], v[60:61] op_sel:[0,1] op_sel_hi:[1,0]
	v_mov_b32_e32 v55, v74
	v_mov_b32_e32 v53, v73
	v_pk_add_f32 v[50:51], v[52:53], v[54:55]
	v_lshlrev_b32_e32 v54, 2, v67
	v_pk_add_f32 v[50:51], v[50:51], v[56:57]
	v_cmp_lt_i32_e32 vcc, v46, v42
	v_add_f32_e32 v50, v50, v51
	s_waitcnt lgkmcnt(0)
	v_add_f32_e32 v51, v58, v59
	ds_bpermute_b32 v49, v49, v50
	ds_bpermute_b32 v52, v70, v51
	v_cndmask_b32_e32 v53, v41, v46, vcc
	v_lshlrev_b32_e32 v56, 2, v53
	v_cmp_lt_i32_e32 vcc, v47, v42
	s_waitcnt lgkmcnt(1)
	v_add_f32_e32 v49, v50, v49
	s_waitcnt lgkmcnt(0)
	v_add_f32_e32 v51, v51, v52
	ds_bpermute_b32 v50, v70, v49
	ds_bpermute_b32 v52, v54, v51
	v_cndmask_b32_e32 v55, v41, v47, vcc
	v_lshlrev_b32_e32 v55, 2, v55
	v_cmp_lt_i32_e32 vcc, v48, v42
	s_waitcnt lgkmcnt(1)
	v_add_f32_e32 v49, v49, v50
	s_waitcnt lgkmcnt(0)
	v_add_f32_e32 v57, v51, v52
	global_load_dwordx4 v[50:53], v[32:33], off
	ds_bpermute_b32 v54, v54, v49
	ds_bpermute_b32 v58, v56, v57
	s_waitcnt lgkmcnt(1)
	v_add_f32_e32 v49, v49, v54
	ds_bpermute_b32 v54, v56, v49
	s_waitcnt lgkmcnt(1)
	v_add_f32_e32 v56, v57, v58
	ds_bpermute_b32 v57, v55, v56
	v_cndmask_b32_e32 v58, v41, v48, vcc
	s_waitcnt lgkmcnt(1)
	v_add_f32_e32 v49, v49, v54
	ds_bpermute_b32 v54, v55, v49
	v_lshlrev_b32_e32 v55, 2, v58
	s_waitcnt lgkmcnt(1)
	v_add_f32_e32 v56, v56, v57
	ds_bpermute_b32 v57, v55, v56
	s_waitcnt lgkmcnt(1)
; __device__ __forceinline__ unsigned pk2(float lo, float hi) { return f2bf(lo) | (f2bf(hi) << 16); }
; template <int MODE> __device__ __forceinline__ void norm_row2(const float* xa, const float* xb, const float* nw, const float* sca, const float* sha, const float* scb, const float* shb, ...
;     ...
;     const float r0 = 1.f / sqrtf(s0 * (1.f / D) + eps), r1 = 1.f / sqrtf(s1 * (1.f / D) + eps);
; #pragma unroll
;     for (int j = 0; j < 4; ++j) { const f32x4 w = ((const f32x4*)nw)[64 * j + lane]; f32x4 ya = va[j] * r0 * w, yb = vb[j] * r1 * w;
;         if (MODE == 0) { const f32x4 ca = ((const f32x4*)sca)[64 * j + lane], ha = ((const f32x4*)sha)[64 * j + lane], cb = ((const f32x4*)scb)[64 * j + lane], hb = ((const f32x4*)shb)[64 * j + lane];
;             ya = ya * (ca + 1.f) + ha; yb = yb * (cb + 1.f) + hb;
;             u32x2 o; o.x = pk2(ya.x, ya.y); o.y = pk2(ya.z, ya.w); ((u32x2*)oa)[64 * j + lane] = o; o.x = pk2(yb.x, yb.y); o.y = pk2(yb.z, yb.w); ((u32x2*)ob)[64 * j + lane] = o; }
;         else { ((f32x4*)fa_)[64 * j + lane] = ya; ((f32x4*)fb_)[64 * j + lane] = yb; } }
	v_add_f32_e32 v49, v49, v54
	ds_bpermute_b32 v54, v55, v49
	s_waitcnt lgkmcnt(1)
	v_add_f32_e32 v55, v56, v57
	v_fmamk_f32 v55, v55, 0x3a800000, v38
	v_mul_f32_e32 v56, 0x4f800000, v55
	v_cmp_gt_f32_e32 vcc, s10, v55
	s_waitcnt lgkmcnt(0)
	v_add_f32_e32 v49, v49, v54
	v_fmamk_f32 v49, v49, 0x3a800000, v38
	v_cndmask_b32_e32 v54, v55, v56, vcc
	v_sqrt_f32_e32 v55, v54
	v_mul_f32_e32 v56, 0x4f800000, v49
	v_cmp_gt_f32_e64 s[0:1], s10, v49
	v_add_u32_e32 v57, -1, v55
	v_add_u32_e32 v58, 1, v55
	v_fma_f32 v59, -v57, v55, v54
	v_fma_f32 v60, -v58, v55, v54
	v_cmp_ge_f32_e64 s[2:3], 0, v59
	v_cndmask_b32_e64 v49, v49, v56, s[0:1]
	v_sqrt_f32_e32 v56, v49
	v_cndmask_b32_e64 v55, v55, v57, s[2:3]
	v_cmp_lt_f32_e64 s[2:3], 0, v60
	v_add_u32_e32 v57, -1, v56
	s_nop 0
	v_cndmask_b32_e64 v55, v55, v58, s[2:3]
	v_mul_f32_e32 v59, 0x37800000, v55
	v_cndmask_b32_e32 v55, v55, v59, vcc
	v_cmp_class_f32_e32 vcc, v54, v39
	v_fma_f32 v60, -v57, v56, v49
	v_add_u32_e32 v58, 1, v56
	v_cndmask_b32_e32 v54, v55, v54, vcc
	v_div_scale_f32 v55, s[2:3], v54, v54, 1.0
	v_rcp_f32_e32 v59, v55
	v_cmp_ge_f32_e32 vcc, 0, v60
	v_fma_f32 v61, -v58, v56, v49
	v_cmp_lt_f32_e64 s[2:3], 0, v61
	v_fma_f32 v60, -v55, v59, 1.0
	v_cndmask_b32_e32 v56, v56, v57, vcc
	v_div_scale_f32 v57, vcc, 1.0, v54, 1.0
	v_fmac_f32_e32 v59, v60, v59
	v_mul_f32_e32 v60, v57, v59
	v_fma_f32 v62, -v55, v60, v57
	v_fmac_f32_e32 v60, v62, v59
	v_cndmask_b32_e64 v56, v56, v58, s[2:3]
	v_fma_f32 v55, -v55, v60, v57
	v_mul_f32_e32 v57, 0x37800000, v56
	v_cndmask_b32_e64 v56, v56, v57, s[0:1]
	v_cmp_class_f32_e64 s[0:1], v49, v39
	v_div_fmas_f32 v55, v55, v59, v60
	v_div_fixup_f32 v54, v55, v54, 1.0
	v_cndmask_b32_e64 v49, v56, v49, s[0:1]
	v_div_scale_f32 v56, s[0:1], v49, v49, 1.0
	v_rcp_f32_e32 v57, v56
	s_nop 0
	v_fma_f32 v55, -v56, v57, 1.0
	v_fmac_f32_e32 v57, v55, v57
	v_div_scale_f32 v55, vcc, 1.0, v49, 1.0
	v_mul_f32_e32 v58, v55, v57
	v_fma_f32 v59, -v56, v58, v55
	v_fmac_f32_e32 v58, v59, v57
	v_fma_f32 v55, -v56, v58, v55
	v_div_fmas_f32 v55, v55, v57, v58
	v_div_fixup_f32 v56, v55, v49, 1.0
	v_pk_mul_f32 v[24:25], v[24:25], v[54:55] op_sel_hi:[1,0]
	v_pk_mul_f32 v[26:27], v[26:27], v[54:55] op_sel_hi:[1,0]
	s_waitcnt vmcnt(0)
	v_pk_mul_f32 v[24:25], v[50:51], v[24:25]
	v_pk_mul_f32 v[26:27], v[52:53], v[26:27]
	v_pk_mul_f32 v[28:29], v[28:29], v[56:57] op_sel_hi:[1,0]
	v_pk_mul_f32 v[30:31], v[30:31], v[56:57] op_sel_hi:[1,0]
	v_pk_mul_f32 v[28:29], v[50:51], v[28:29]
	v_pk_mul_f32 v[30:31], v[52:53], v[30:31]
	global_store_dwordx4 v40, v[24:27], s[6:7] nt
	global_store_dwordx4 v[36:37], v[28:31], off nt
	global_load_dwordx4 v[24:27], v[32:33], off offset:1024
	v_pk_mul_f32 v[18:19], v[18:19], v[54:55] op_sel_hi:[1,0]
	v_pk_mul_f32 v[16:17], v[16:17], v[54:55] op_sel_hi:[1,0]
	v_pk_mul_f32 v[22:23], v[22:23], v[56:57] op_sel_hi:[1,0]
	v_pk_mul_f32 v[20:21], v[20:21], v[56:57] op_sel_hi:[1,0]
	v_pk_mul_f32 v[10:11], v[10:11], v[54:55] op_sel_hi:[1,0]
	v_pk_mul_f32 v[8:9], v[8:9], v[54:55] op_sel_hi:[1,0]
	v_pk_mul_f32 v[14:15], v[14:15], v[56:57] op_sel_hi:[1,0]
	v_pk_mul_f32 v[12:13], v[12:13], v[56:57] op_sel_hi:[1,0]
	v_pk_mul_f32 v[6:7], v[6:7], v[54:55] op_sel_hi:[1,0]
	v_pk_mul_f32 v[4:5], v[4:5], v[54:55] op_sel_hi:[1,0]
	v_pk_mul_f32 v[2:3], v[2:3], v[56:57] op_sel_hi:[1,0]
	v_pk_mul_f32 v[0:1], v[0:1], v[56:57] op_sel_hi:[1,0]
	s_waitcnt vmcnt(0)
	v_pk_mul_f32 v[16:17], v[24:25], v[16:17]
	v_pk_mul_f32 v[18:19], v[26:27], v[18:19]
	v_pk_mul_f32 v[20:21], v[24:25], v[20:21]
	v_pk_mul_f32 v[22:23], v[26:27], v[22:23]
	global_store_dwordx4 v40, v[16:19], s[6:7] offset:1024 nt
	global_store_dwordx4 v[36:37], v[20:23], off offset:1024 nt
	global_load_dwordx4 v[16:19], v[32:33], off offset:2048
	s_waitcnt vmcnt(0)
	v_pk_mul_f32 v[8:9], v[16:17], v[8:9]
	v_pk_mul_f32 v[10:11], v[18:19], v[10:11]
	v_pk_mul_f32 v[12:13], v[16:17], v[12:13]
	v_pk_mul_f32 v[14:15], v[18:19], v[14:15]
	global_store_dwordx4 v40, v[8:11], s[6:7] offset:2048 nt
	global_store_dwordx4 v[36:37], v[12:15], off offset:2048 nt
	global_load_dwordx4 v[8:11], v[32:33], off offset:3072
	s_waitcnt vmcnt(0)
	v_pk_mul_f32 v[4:5], v[4:5], v[8:9]
	v_pk_mul_f32 v[6:7], v[6:7], v[10:11]
	v_pk_mul_f32 v[0:1], v[0:1], v[8:9]
	v_pk_mul_f32 v[2:3], v[2:3], v[10:11]
	global_store_dwordx4 v40, v[4:7], s[6:7] offset:3072 nt
	s_branch .LBB0_1237
